# rewrote split-KV combine of sample diff-attention: batched pipelined loads (7 outputs deep) instead of one round trip per pair; all 64 lanes useful
# speedup vs baseline: 1.0199x; 1.0199x over previous
.LBB0_696:
	s_or_b64 exec, exec, s[0:1]
	v_readlane_b32 s0, v255, 6
	s_waitcnt lgkmcnt(0)
	s_barrier
	v_mov_b32_e32 v0, s0
	ds_read_b32 v0, v0
	s_cmp_gt_u32 s15, 63
	s_cselect_b64 s[0:1], -1, 0
	s_waitcnt lgkmcnt(0)
	v_cmp_ne_u32_e32 vcc, 3, v0
	s_or_b64 s[0:1], s[0:1], vcc
	s_and_b64 vcc, exec, s[0:1]
	s_cbranch_vccnz .LBB0_508
	s_mul_i32 s70, s10, 0x8400
	s_lshl_b64 s[0:1], s[70:71], 2
	v_readlane_b32 s6, v254, 56
	s_add_u32 s0, s6, s0
	v_readlane_b32 s6, v254, 58
	s_addc_u32 s1, s6, s1
	v_and_b32_e32 v0, 16, v219
	v_sub_u32_e32 v2, v219, v0
	v_lshlrev_b32_e32 v2, 2, v2
	v_lshl_add_u32 v2, v0, 9, v2
	v_add_u32_e32 v2, 0x1000, v2
	v_add_u32_e32 v3, 0x4200, v2
	v_add_u32_e32 v4, 0x4200, v3
	v_add_u32_e32 v5, 0x4200, v4
	v_add_u32_e32 v6, 0x4200, v5
	v_add_u32_e32 v7, 0x4200, v6
	v_add_u32_e32 v8, 0x4200, v7
	v_add_u32_e32 v9, 0x4200, v8
	v_lshlrev_b32_e32 v0, 9, v0
	v_sub_u32_e32 v0, 0x4000, v0
	v_add_u32_e32 v35, v2, v0
	v_add_u32_e32 v36, v3, v0
	v_add_u32_e32 v37, v4, v0
	v_add_u32_e32 v38, v5, v0
	v_add_u32_e32 v39, v6, v0
	v_add_u32_e32 v40, v7, v0
	v_add_u32_e32 v41, v8, v0
	v_add_u32_e32 v42, v9, v0
	global_load_dword v19, v35, s[0:1] offset:-4096
	global_load_dword v27, v35, s[0:1] offset:-3840
	global_load_dword v20, v36, s[0:1] offset:-4096
	global_load_dword v28, v36, s[0:1] offset:-3840
	global_load_dword v21, v37, s[0:1] offset:-4096
	global_load_dword v29, v37, s[0:1] offset:-3840
	global_load_dword v22, v38, s[0:1] offset:-4096
	global_load_dword v30, v38, s[0:1] offset:-3840
	global_load_dword v23, v39, s[0:1] offset:-4096
	global_load_dword v31, v39, s[0:1] offset:-3840
	global_load_dword v24, v40, s[0:1] offset:-4096
	global_load_dword v32, v40, s[0:1] offset:-3840
	global_load_dword v25, v41, s[0:1] offset:-4096
	global_load_dword v33, v41, s[0:1] offset:-3840
	global_load_dword v26, v42, s[0:1] offset:-4096
	global_load_dword v34, v42, s[0:1] offset:-3840
	global_load_dword v51, v2, s[0:1] offset:-4096
	global_load_dword v52, v3, s[0:1] offset:-4096
	global_load_dword v53, v4, s[0:1] offset:-4096
	global_load_dword v54, v5, s[0:1] offset:-4096
	global_load_dword v55, v6, s[0:1] offset:-4096
	global_load_dword v56, v7, s[0:1] offset:-4096
	global_load_dword v57, v8, s[0:1] offset:-4096
	global_load_dword v58, v9, s[0:1] offset:-4096
	global_load_dword v59, v2, s[0:1] offset:-3840
	global_load_dword v60, v3, s[0:1] offset:-3840
	global_load_dword v61, v4, s[0:1] offset:-3840
	global_load_dword v62, v5, s[0:1] offset:-3840
	global_load_dword v63, v6, s[0:1] offset:-3840
	global_load_dword v64, v7, s[0:1] offset:-3840
	global_load_dword v65, v8, s[0:1] offset:-3840
	global_load_dword v66, v9, s[0:1] offset:-3840
	global_load_dword v67, v2, s[0:1] offset:-3584
	global_load_dword v68, v3, s[0:1] offset:-3584
	global_load_dword v69, v4, s[0:1] offset:-3584
	global_load_dword v70, v5, s[0:1] offset:-3584
	global_load_dword v71, v6, s[0:1] offset:-3584
	global_load_dword v72, v7, s[0:1] offset:-3584
	global_load_dword v73, v8, s[0:1] offset:-3584
	global_load_dword v74, v9, s[0:1] offset:-3584
	global_load_dword v75, v2, s[0:1] offset:-3328
	global_load_dword v76, v3, s[0:1] offset:-3328
	global_load_dword v77, v4, s[0:1] offset:-3328
	global_load_dword v78, v5, s[0:1] offset:-3328
	global_load_dword v79, v6, s[0:1] offset:-3328
	global_load_dword v80, v7, s[0:1] offset:-3328
	global_load_dword v81, v8, s[0:1] offset:-3328
	global_load_dword v82, v9, s[0:1] offset:-3328
	global_load_dword v83, v2, s[0:1] offset:-3072
	global_load_dword v84, v3, s[0:1] offset:-3072
	global_load_dword v85, v4, s[0:1] offset:-3072
	global_load_dword v86, v5, s[0:1] offset:-3072
	global_load_dword v87, v6, s[0:1] offset:-3072
	global_load_dword v88, v7, s[0:1] offset:-3072
	global_load_dword v89, v8, s[0:1] offset:-3072
	global_load_dword v90, v9, s[0:1] offset:-3072
	global_load_dword v91, v2, s[0:1] offset:-2816
	global_load_dword v92, v3, s[0:1] offset:-2816
	global_load_dword v93, v4, s[0:1] offset:-2816
	global_load_dword v94, v5, s[0:1] offset:-2816
	global_load_dword v95, v6, s[0:1] offset:-2816
	global_load_dword v96, v7, s[0:1] offset:-2816
	global_load_dword v97, v8, s[0:1] offset:-2816
	global_load_dword v98, v9, s[0:1] offset:-2816
	global_load_dword v99, v2, s[0:1] offset:-2560
	global_load_dword v100, v3, s[0:1] offset:-2560
	global_load_dword v101, v4, s[0:1] offset:-2560
	global_load_dword v102, v5, s[0:1] offset:-2560
	global_load_dword v103, v6, s[0:1] offset:-2560
	global_load_dword v104, v7, s[0:1] offset:-2560
	global_load_dword v105, v8, s[0:1] offset:-2560
	global_load_dword v106, v9, s[0:1] offset:-2560
	s_waitcnt vmcnt(56)
	s_mov_b32 s6, 0xf149f2ca
	v_max3_f32 v43, v19, s6, v21
	v_max3_f32 v43, v43, v23, v25
	v_max3_f32 v44, v20, s6, v22
	v_max3_f32 v44, v44, v24, v26
	v_sub_f32_e32 v10, v19, v43
	v_mul_f32_e32 v10, 0x3e38aa3b, v10
	v_exp_f32_e32 v10, v10
	v_sub_f32_e32 v11, v20, v44
	v_mul_f32_e32 v11, 0x3e38aa3b, v11
	v_exp_f32_e32 v11, v11
	v_sub_f32_e32 v12, v21, v43
	v_mul_f32_e32 v12, 0x3e38aa3b, v12
	v_exp_f32_e32 v12, v12
	v_sub_f32_e32 v13, v22, v44
	v_mul_f32_e32 v13, 0x3e38aa3b, v13
	v_exp_f32_e32 v13, v13
	v_sub_f32_e32 v14, v23, v43
	v_mul_f32_e32 v14, 0x3e38aa3b, v14
	v_exp_f32_e32 v14, v14
	v_sub_f32_e32 v15, v24, v44
	v_mul_f32_e32 v15, 0x3e38aa3b, v15
	v_exp_f32_e32 v15, v15
	v_sub_f32_e32 v16, v25, v43
	v_mul_f32_e32 v16, 0x3e38aa3b, v16
	v_exp_f32_e32 v16, v16
	v_sub_f32_e32 v17, v26, v44
	v_mul_f32_e32 v17, 0x3e38aa3b, v17
	v_exp_f32_e32 v17, v17
	s_nop 0
	v_mul_f32_e32 v45, v10, v27
	v_mul_f32_e32 v47, v12, v29
	v_add_f32_e32 v45, v45, v47
	v_mul_f32_e32 v47, v14, v31
	v_add_f32_e32 v45, v45, v47
	v_mul_f32_e32 v47, v16, v33
	v_add_f32_e32 v45, v45, v47
	v_mul_f32_e32 v46, v11, v28
	v_mul_f32_e32 v47, v13, v30
	v_add_f32_e32 v46, v46, v47
	v_mul_f32_e32 v47, v15, v32
	v_add_f32_e32 v46, v46, v47
	v_mul_f32_e32 v47, v17, v34
	v_add_f32_e32 v46, v46, v47
	v_div_scale_f32 v47, s[6:7], v45, v45, 1.0
	v_rcp_f32_e32 v48, v47
	s_nop 0
	v_fma_f32 v49, -v47, v48, 1.0
	v_fmac_f32_e32 v48, v49, v48
	v_div_scale_f32 v49, vcc, 1.0, v45, 1.0
	v_mul_f32_e32 v50, v49, v48
	v_fma_f32 v35, -v47, v50, v49
	v_fmac_f32_e32 v50, v35, v48
	v_fma_f32 v47, -v47, v50, v49
	s_nop 1
	v_div_fmas_f32 v47, v47, v48, v50
	v_div_fixup_f32 v45, v47, v45, 1.0
	v_div_scale_f32 v47, s[6:7], v46, v46, v197
	v_rcp_f32_e32 v48, v47
	s_nop 0
	v_fma_f32 v49, -v47, v48, 1.0
	v_fmac_f32_e32 v48, v49, v48
	v_div_scale_f32 v49, vcc, v197, v46, v197
	v_mul_f32_e32 v50, v49, v48
	v_fma_f32 v35, -v47, v50, v49
	v_fmac_f32_e32 v50, v35, v48
	v_fma_f32 v47, -v47, v50, v49
	s_nop 1
	v_div_fmas_f32 v47, v47, v48, v50
	v_div_fixup_f32 v46, v47, v46, v197
	v_mul_f32_e32 v10, v10, v45
	v_mul_f32_e32 v11, v11, v46
	v_mul_f32_e32 v12, v12, v45
	v_mul_f32_e32 v13, v13, v46
	v_mul_f32_e32 v14, v14, v45
	v_mul_f32_e32 v15, v15, v46
	v_mul_f32_e32 v16, v16, v45
	v_mul_f32_e32 v17, v17, v46
	v_mov_b32_e32 v18, 0
	s_waitcnt vmcnt(48)
	v_mul_f32_e32 v0, v11, v52
	v_fma_f32 v19, v10, v51, -v0
	v_mul_f32_e32 v0, v13, v54
	v_fma_f32 v0, v12, v53, -v0
	v_add_f32_e32 v19, v19, v0
	v_mul_f32_e32 v0, v15, v56
	v_fma_f32 v0, v14, v55, -v0
	v_add_f32_e32 v19, v19, v0
	v_mul_f32_e32 v0, v17, v58
	v_fma_f32 v0, v16, v57, -v0
	v_add_f32_e32 v19, v19, v0
	v_fmac_f32_e32 v18, v19, v19
	global_load_dword v51, v2, s[0:1] offset:-2304
	global_load_dword v52, v3, s[0:1] offset:-2304
	global_load_dword v53, v4, s[0:1] offset:-2304
	global_load_dword v54, v5, s[0:1] offset:-2304
	global_load_dword v55, v6, s[0:1] offset:-2304
	global_load_dword v56, v7, s[0:1] offset:-2304
	global_load_dword v57, v8, s[0:1] offset:-2304
	global_load_dword v58, v9, s[0:1] offset:-2304
	s_waitcnt vmcnt(48)
	v_mul_f32_e32 v0, v11, v60
	v_fma_f32 v20, v10, v59, -v0
	v_mul_f32_e32 v0, v13, v62
	v_fma_f32 v0, v12, v61, -v0
	v_add_f32_e32 v20, v20, v0
	v_mul_f32_e32 v0, v15, v64
	v_fma_f32 v0, v14, v63, -v0
	v_add_f32_e32 v20, v20, v0
	v_mul_f32_e32 v0, v17, v66
	v_fma_f32 v0, v16, v65, -v0
	v_add_f32_e32 v20, v20, v0
	v_fmac_f32_e32 v18, v20, v20
	global_load_dword v59, v2, s[0:1] offset:-2048
	global_load_dword v60, v3, s[0:1] offset:-2048
	global_load_dword v61, v4, s[0:1] offset:-2048
	global_load_dword v62, v5, s[0:1] offset:-2048
	global_load_dword v63, v6, s[0:1] offset:-2048
	global_load_dword v64, v7, s[0:1] offset:-2048
	global_load_dword v65, v8, s[0:1] offset:-2048
	global_load_dword v66, v9, s[0:1] offset:-2048
	s_waitcnt vmcnt(48)
	v_mul_f32_e32 v0, v11, v68
	v_fma_f32 v21, v10, v67, -v0
	v_mul_f32_e32 v0, v13, v70
	v_fma_f32 v0, v12, v69, -v0
	v_add_f32_e32 v21, v21, v0
	v_mul_f32_e32 v0, v15, v72
	v_fma_f32 v0, v14, v71, -v0
	v_add_f32_e32 v21, v21, v0
	v_mul_f32_e32 v0, v17, v74
	v_fma_f32 v0, v16, v73, -v0
	v_add_f32_e32 v21, v21, v0
	v_fmac_f32_e32 v18, v21, v21
	global_load_dword v67, v2, s[0:1] offset:-1792
	global_load_dword v68, v3, s[0:1] offset:-1792
	global_load_dword v69, v4, s[0:1] offset:-1792
	global_load_dword v70, v5, s[0:1] offset:-1792
	global_load_dword v71, v6, s[0:1] offset:-1792
	global_load_dword v72, v7, s[0:1] offset:-1792
	global_load_dword v73, v8, s[0:1] offset:-1792
	global_load_dword v74, v9, s[0:1] offset:-1792
	s_waitcnt vmcnt(48)
	v_mul_f32_e32 v0, v11, v76
	v_fma_f32 v22, v10, v75, -v0
	v_mul_f32_e32 v0, v13, v78
	v_fma_f32 v0, v12, v77, -v0
	v_add_f32_e32 v22, v22, v0
	v_mul_f32_e32 v0, v15, v80
	v_fma_f32 v0, v14, v79, -v0
	v_add_f32_e32 v22, v22, v0
	v_mul_f32_e32 v0, v17, v82
	v_fma_f32 v0, v16, v81, -v0
	v_add_f32_e32 v22, v22, v0
	v_fmac_f32_e32 v18, v22, v22
	global_load_dword v75, v2, s[0:1] offset:-1536
	global_load_dword v76, v3, s[0:1] offset:-1536
	global_load_dword v77, v4, s[0:1] offset:-1536
	global_load_dword v78, v5, s[0:1] offset:-1536
	global_load_dword v79, v6, s[0:1] offset:-1536
	global_load_dword v80, v7, s[0:1] offset:-1536
	global_load_dword v81, v8, s[0:1] offset:-1536
	global_load_dword v82, v9, s[0:1] offset:-1536
	s_waitcnt vmcnt(48)
	v_mul_f32_e32 v0, v11, v84
	v_fma_f32 v23, v10, v83, -v0
	v_mul_f32_e32 v0, v13, v86
	v_fma_f32 v0, v12, v85, -v0
	v_add_f32_e32 v23, v23, v0
	v_mul_f32_e32 v0, v15, v88
	v_fma_f32 v0, v14, v87, -v0
	v_add_f32_e32 v23, v23, v0
	v_mul_f32_e32 v0, v17, v90
	v_fma_f32 v0, v16, v89, -v0
	v_add_f32_e32 v23, v23, v0
	v_fmac_f32_e32 v18, v23, v23
	global_load_dword v83, v2, s[0:1] offset:-1280
	global_load_dword v84, v3, s[0:1] offset:-1280
	global_load_dword v85, v4, s[0:1] offset:-1280
	global_load_dword v86, v5, s[0:1] offset:-1280
	global_load_dword v87, v6, s[0:1] offset:-1280
	global_load_dword v88, v7, s[0:1] offset:-1280
	global_load_dword v89, v8, s[0:1] offset:-1280
	global_load_dword v90, v9, s[0:1] offset:-1280
	s_waitcnt vmcnt(48)
	v_mul_f32_e32 v0, v11, v92
	v_fma_f32 v24, v10, v91, -v0
	v_mul_f32_e32 v0, v13, v94
	v_fma_f32 v0, v12, v93, -v0
	v_add_f32_e32 v24, v24, v0
	v_mul_f32_e32 v0, v15, v96
	v_fma_f32 v0, v14, v95, -v0
	v_add_f32_e32 v24, v24, v0
	v_mul_f32_e32 v0, v17, v98
	v_fma_f32 v0, v16, v97, -v0
	v_add_f32_e32 v24, v24, v0
	v_fmac_f32_e32 v18, v24, v24
	global_load_dword v91, v2, s[0:1] offset:-1024
	global_load_dword v92, v3, s[0:1] offset:-1024
	global_load_dword v93, v4, s[0:1] offset:-1024
	global_load_dword v94, v5, s[0:1] offset:-1024
	global_load_dword v95, v6, s[0:1] offset:-1024
	global_load_dword v96, v7, s[0:1] offset:-1024
	global_load_dword v97, v8, s[0:1] offset:-1024
	global_load_dword v98, v9, s[0:1] offset:-1024
	s_waitcnt vmcnt(48)
	v_mul_f32_e32 v0, v11, v100
	v_fma_f32 v25, v10, v99, -v0
	v_mul_f32_e32 v0, v13, v102
	v_fma_f32 v0, v12, v101, -v0
	v_add_f32_e32 v25, v25, v0
	v_mul_f32_e32 v0, v15, v104
	v_fma_f32 v0, v14, v103, -v0
	v_add_f32_e32 v25, v25, v0
	v_mul_f32_e32 v0, v17, v106
	v_fma_f32 v0, v16, v105, -v0
	v_add_f32_e32 v25, v25, v0
	v_fmac_f32_e32 v18, v25, v25
	global_load_dword v99, v2, s[0:1] offset:-768
	global_load_dword v100, v3, s[0:1] offset:-768
	global_load_dword v101, v4, s[0:1] offset:-768
	global_load_dword v102, v5, s[0:1] offset:-768
	global_load_dword v103, v6, s[0:1] offset:-768
	global_load_dword v104, v7, s[0:1] offset:-768
	global_load_dword v105, v8, s[0:1] offset:-768
	global_load_dword v106, v9, s[0:1] offset:-768
	s_waitcnt vmcnt(48)
	v_mul_f32_e32 v0, v11, v52
	v_fma_f32 v26, v10, v51, -v0
	v_mul_f32_e32 v0, v13, v54
	v_fma_f32 v0, v12, v53, -v0
	v_add_f32_e32 v26, v26, v0
	v_mul_f32_e32 v0, v15, v56
	v_fma_f32 v0, v14, v55, -v0
	v_add_f32_e32 v26, v26, v0
	v_mul_f32_e32 v0, v17, v58
	v_fma_f32 v0, v16, v57, -v0
	v_add_f32_e32 v26, v26, v0
	v_fmac_f32_e32 v18, v26, v26
	global_load_dword v51, v2, s[0:1] offset:-512
	global_load_dword v52, v3, s[0:1] offset:-512
	global_load_dword v53, v4, s[0:1] offset:-512
	global_load_dword v54, v5, s[0:1] offset:-512
	global_load_dword v55, v6, s[0:1] offset:-512
	global_load_dword v56, v7, s[0:1] offset:-512
	global_load_dword v57, v8, s[0:1] offset:-512
	global_load_dword v58, v9, s[0:1] offset:-512
	s_waitcnt vmcnt(48)
	v_mul_f32_e32 v0, v11, v60
	v_fma_f32 v27, v10, v59, -v0
	v_mul_f32_e32 v0, v13, v62
	v_fma_f32 v0, v12, v61, -v0
	v_add_f32_e32 v27, v27, v0
	v_mul_f32_e32 v0, v15, v64
	v_fma_f32 v0, v14, v63, -v0
	v_add_f32_e32 v27, v27, v0
	v_mul_f32_e32 v0, v17, v66
	v_fma_f32 v0, v16, v65, -v0
	v_add_f32_e32 v27, v27, v0
	v_fmac_f32_e32 v18, v27, v27
	global_load_dword v59, v2, s[0:1] offset:-256
	global_load_dword v60, v3, s[0:1] offset:-256
	global_load_dword v61, v4, s[0:1] offset:-256
	global_load_dword v62, v5, s[0:1] offset:-256
	global_load_dword v63, v6, s[0:1] offset:-256
	global_load_dword v64, v7, s[0:1] offset:-256
	global_load_dword v65, v8, s[0:1] offset:-256
	global_load_dword v66, v9, s[0:1] offset:-256
	s_waitcnt vmcnt(48)
	v_mul_f32_e32 v0, v11, v68
	v_fma_f32 v28, v10, v67, -v0
	v_mul_f32_e32 v0, v13, v70
	v_fma_f32 v0, v12, v69, -v0
	v_add_f32_e32 v28, v28, v0
	v_mul_f32_e32 v0, v15, v72
	v_fma_f32 v0, v14, v71, -v0
	v_add_f32_e32 v28, v28, v0
	v_mul_f32_e32 v0, v17, v74
	v_fma_f32 v0, v16, v73, -v0
	v_add_f32_e32 v28, v28, v0
	v_fmac_f32_e32 v18, v28, v28
	global_load_dword v67, v2, s[0:1] offset:0
	global_load_dword v68, v3, s[0:1] offset:0
	global_load_dword v69, v4, s[0:1] offset:0
	global_load_dword v70, v5, s[0:1] offset:0
	global_load_dword v71, v6, s[0:1] offset:0
	global_load_dword v72, v7, s[0:1] offset:0
	global_load_dword v73, v8, s[0:1] offset:0
	global_load_dword v74, v9, s[0:1] offset:0
	s_waitcnt vmcnt(48)
	v_mul_f32_e32 v0, v11, v76
	v_fma_f32 v29, v10, v75, -v0
	v_mul_f32_e32 v0, v13, v78
	v_fma_f32 v0, v12, v77, -v0
	v_add_f32_e32 v29, v29, v0
	v_mul_f32_e32 v0, v15, v80
	v_fma_f32 v0, v14, v79, -v0
	v_add_f32_e32 v29, v29, v0
	v_mul_f32_e32 v0, v17, v82
	v_fma_f32 v0, v16, v81, -v0
	v_add_f32_e32 v29, v29, v0
	v_fmac_f32_e32 v18, v29, v29
	global_load_dword v75, v2, s[0:1] offset:256
	global_load_dword v76, v3, s[0:1] offset:256
	global_load_dword v77, v4, s[0:1] offset:256
	global_load_dword v78, v5, s[0:1] offset:256
	global_load_dword v79, v6, s[0:1] offset:256
	global_load_dword v80, v7, s[0:1] offset:256
	global_load_dword v81, v8, s[0:1] offset:256
	global_load_dword v82, v9, s[0:1] offset:256
	s_waitcnt vmcnt(48)
	v_mul_f32_e32 v0, v11, v84
	v_fma_f32 v30, v10, v83, -v0
	v_mul_f32_e32 v0, v13, v86
	v_fma_f32 v0, v12, v85, -v0
	v_add_f32_e32 v30, v30, v0
	v_mul_f32_e32 v0, v15, v88
	v_fma_f32 v0, v14, v87, -v0
	v_add_f32_e32 v30, v30, v0
	v_mul_f32_e32 v0, v17, v90
	v_fma_f32 v0, v16, v89, -v0
	v_add_f32_e32 v30, v30, v0
	v_fmac_f32_e32 v18, v30, v30
	global_load_dword v83, v2, s[0:1] offset:512
	global_load_dword v84, v3, s[0:1] offset:512
	global_load_dword v85, v4, s[0:1] offset:512
	global_load_dword v86, v5, s[0:1] offset:512
	global_load_dword v87, v6, s[0:1] offset:512
	global_load_dword v88, v7, s[0:1] offset:512
	global_load_dword v89, v8, s[0:1] offset:512
	global_load_dword v90, v9, s[0:1] offset:512
	s_waitcnt vmcnt(48)
	v_mul_f32_e32 v0, v11, v92
	v_fma_f32 v31, v10, v91, -v0
	v_mul_f32_e32 v0, v13, v94
	v_fma_f32 v0, v12, v93, -v0
	v_add_f32_e32 v31, v31, v0
	v_mul_f32_e32 v0, v15, v96
	v_fma_f32 v0, v14, v95, -v0
	v_add_f32_e32 v31, v31, v0
	v_mul_f32_e32 v0, v17, v98
	v_fma_f32 v0, v16, v97, -v0
	v_add_f32_e32 v31, v31, v0
	v_fmac_f32_e32 v18, v31, v31
	global_load_dword v91, v2, s[0:1] offset:768
	global_load_dword v92, v3, s[0:1] offset:768
	global_load_dword v93, v4, s[0:1] offset:768
	global_load_dword v94, v5, s[0:1] offset:768
	global_load_dword v95, v6, s[0:1] offset:768
	global_load_dword v96, v7, s[0:1] offset:768
	global_load_dword v97, v8, s[0:1] offset:768
	global_load_dword v98, v9, s[0:1] offset:768
	s_waitcnt vmcnt(48)
	v_mul_f32_e32 v0, v11, v100
	v_fma_f32 v32, v10, v99, -v0
	v_mul_f32_e32 v0, v13, v102
	v_fma_f32 v0, v12, v101, -v0
	v_add_f32_e32 v32, v32, v0
	v_mul_f32_e32 v0, v15, v104
	v_fma_f32 v0, v14, v103, -v0
	v_add_f32_e32 v32, v32, v0
	v_mul_f32_e32 v0, v17, v106
	v_fma_f32 v0, v16, v105, -v0
	v_add_f32_e32 v32, v32, v0
	v_fmac_f32_e32 v18, v32, v32
	global_load_dword v99, v2, s[0:1] offset:1024
	global_load_dword v100, v3, s[0:1] offset:1024
	global_load_dword v101, v4, s[0:1] offset:1024
	global_load_dword v102, v5, s[0:1] offset:1024
	global_load_dword v103, v6, s[0:1] offset:1024
	global_load_dword v104, v7, s[0:1] offset:1024
	global_load_dword v105, v8, s[0:1] offset:1024
	global_load_dword v106, v9, s[0:1] offset:1024
	s_waitcnt vmcnt(48)
	v_mul_f32_e32 v0, v11, v52
	v_fma_f32 v33, v10, v51, -v0
	v_mul_f32_e32 v0, v13, v54
	v_fma_f32 v0, v12, v53, -v0
	v_add_f32_e32 v33, v33, v0
	v_mul_f32_e32 v0, v15, v56
	v_fma_f32 v0, v14, v55, -v0
	v_add_f32_e32 v33, v33, v0
	v_mul_f32_e32 v0, v17, v58
	v_fma_f32 v0, v16, v57, -v0
	v_add_f32_e32 v33, v33, v0
	v_fmac_f32_e32 v18, v33, v33
	global_load_dword v51, v2, s[0:1] offset:1280
	global_load_dword v52, v3, s[0:1] offset:1280
	global_load_dword v53, v4, s[0:1] offset:1280
	global_load_dword v54, v5, s[0:1] offset:1280
	global_load_dword v55, v6, s[0:1] offset:1280
	global_load_dword v56, v7, s[0:1] offset:1280
	global_load_dword v57, v8, s[0:1] offset:1280
	global_load_dword v58, v9, s[0:1] offset:1280
	s_waitcnt vmcnt(48)
	v_mul_f32_e32 v0, v11, v60
	v_fma_f32 v34, v10, v59, -v0
	v_mul_f32_e32 v0, v13, v62
	v_fma_f32 v0, v12, v61, -v0
	v_add_f32_e32 v34, v34, v0
	v_mul_f32_e32 v0, v15, v64
	v_fma_f32 v0, v14, v63, -v0
	v_add_f32_e32 v34, v34, v0
	v_mul_f32_e32 v0, v17, v66
	v_fma_f32 v0, v16, v65, -v0
	v_add_f32_e32 v34, v34, v0
	v_fmac_f32_e32 v18, v34, v34
	global_load_dword v59, v2, s[0:1] offset:1536
	global_load_dword v60, v3, s[0:1] offset:1536
	global_load_dword v61, v4, s[0:1] offset:1536
	global_load_dword v62, v5, s[0:1] offset:1536
	global_load_dword v63, v6, s[0:1] offset:1536
	global_load_dword v64, v7, s[0:1] offset:1536
	global_load_dword v65, v8, s[0:1] offset:1536
	global_load_dword v66, v9, s[0:1] offset:1536
	s_waitcnt vmcnt(48)
	v_mul_f32_e32 v0, v11, v68
	v_fma_f32 v35, v10, v67, -v0
	v_mul_f32_e32 v0, v13, v70
	v_fma_f32 v0, v12, v69, -v0
	v_add_f32_e32 v35, v35, v0
	v_mul_f32_e32 v0, v15, v72
	v_fma_f32 v0, v14, v71, -v0
	v_add_f32_e32 v35, v35, v0
	v_mul_f32_e32 v0, v17, v74
	v_fma_f32 v0, v16, v73, -v0
	v_add_f32_e32 v35, v35, v0
	v_fmac_f32_e32 v18, v35, v35
	global_load_dword v67, v2, s[0:1] offset:1792
	global_load_dword v68, v3, s[0:1] offset:1792
	global_load_dword v69, v4, s[0:1] offset:1792
	global_load_dword v70, v5, s[0:1] offset:1792
	global_load_dword v71, v6, s[0:1] offset:1792
	global_load_dword v72, v7, s[0:1] offset:1792
	global_load_dword v73, v8, s[0:1] offset:1792
	global_load_dword v74, v9, s[0:1] offset:1792
	s_waitcnt vmcnt(48)
	v_mul_f32_e32 v0, v11, v76
	v_fma_f32 v36, v10, v75, -v0
	v_mul_f32_e32 v0, v13, v78
	v_fma_f32 v0, v12, v77, -v0
	v_add_f32_e32 v36, v36, v0
	v_mul_f32_e32 v0, v15, v80
	v_fma_f32 v0, v14, v79, -v0
	v_add_f32_e32 v36, v36, v0
	v_mul_f32_e32 v0, v17, v82
	v_fma_f32 v0, v16, v81, -v0
	v_add_f32_e32 v36, v36, v0
	v_fmac_f32_e32 v18, v36, v36
	global_load_dword v75, v2, s[0:1] offset:2048
	global_load_dword v76, v3, s[0:1] offset:2048
	global_load_dword v77, v4, s[0:1] offset:2048
	global_load_dword v78, v5, s[0:1] offset:2048
	global_load_dword v79, v6, s[0:1] offset:2048
	global_load_dword v80, v7, s[0:1] offset:2048
	global_load_dword v81, v8, s[0:1] offset:2048
	global_load_dword v82, v9, s[0:1] offset:2048
	s_waitcnt vmcnt(48)
	v_mul_f32_e32 v0, v11, v84
	v_fma_f32 v37, v10, v83, -v0
	v_mul_f32_e32 v0, v13, v86
	v_fma_f32 v0, v12, v85, -v0
	v_add_f32_e32 v37, v37, v0
	v_mul_f32_e32 v0, v15, v88
	v_fma_f32 v0, v14, v87, -v0
	v_add_f32_e32 v37, v37, v0
	v_mul_f32_e32 v0, v17, v90
	v_fma_f32 v0, v16, v89, -v0
	v_add_f32_e32 v37, v37, v0
	v_fmac_f32_e32 v18, v37, v37
	global_load_dword v83, v2, s[0:1] offset:2304
	global_load_dword v84, v3, s[0:1] offset:2304
	global_load_dword v85, v4, s[0:1] offset:2304
	global_load_dword v86, v5, s[0:1] offset:2304
	global_load_dword v87, v6, s[0:1] offset:2304
	global_load_dword v88, v7, s[0:1] offset:2304
	global_load_dword v89, v8, s[0:1] offset:2304
	global_load_dword v90, v9, s[0:1] offset:2304
	s_waitcnt vmcnt(48)
	v_mul_f32_e32 v0, v11, v92
	v_fma_f32 v38, v10, v91, -v0
	v_mul_f32_e32 v0, v13, v94
	v_fma_f32 v0, v12, v93, -v0
	v_add_f32_e32 v38, v38, v0
	v_mul_f32_e32 v0, v15, v96
	v_fma_f32 v0, v14, v95, -v0
	v_add_f32_e32 v38, v38, v0
	v_mul_f32_e32 v0, v17, v98
	v_fma_f32 v0, v16, v97, -v0
	v_add_f32_e32 v38, v38, v0
	v_fmac_f32_e32 v18, v38, v38
	global_load_dword v91, v2, s[0:1] offset:2560
	global_load_dword v92, v3, s[0:1] offset:2560
	global_load_dword v93, v4, s[0:1] offset:2560
	global_load_dword v94, v5, s[0:1] offset:2560
	global_load_dword v95, v6, s[0:1] offset:2560
	global_load_dword v96, v7, s[0:1] offset:2560
	global_load_dword v97, v8, s[0:1] offset:2560
	global_load_dword v98, v9, s[0:1] offset:2560
	s_waitcnt vmcnt(48)
	v_mul_f32_e32 v0, v11, v100
	v_fma_f32 v39, v10, v99, -v0
	v_mul_f32_e32 v0, v13, v102
	v_fma_f32 v0, v12, v101, -v0
	v_add_f32_e32 v39, v39, v0
	v_mul_f32_e32 v0, v15, v104
	v_fma_f32 v0, v14, v103, -v0
	v_add_f32_e32 v39, v39, v0
	v_mul_f32_e32 v0, v17, v106
	v_fma_f32 v0, v16, v105, -v0
	v_add_f32_e32 v39, v39, v0
	v_fmac_f32_e32 v18, v39, v39
	global_load_dword v99, v2, s[0:1] offset:2816
	global_load_dword v100, v3, s[0:1] offset:2816
	global_load_dword v101, v4, s[0:1] offset:2816
	global_load_dword v102, v5, s[0:1] offset:2816
	global_load_dword v103, v6, s[0:1] offset:2816
	global_load_dword v104, v7, s[0:1] offset:2816
	global_load_dword v105, v8, s[0:1] offset:2816
	global_load_dword v106, v9, s[0:1] offset:2816
	s_waitcnt vmcnt(48)
	v_mul_f32_e32 v0, v11, v52
	v_fma_f32 v40, v10, v51, -v0
	v_mul_f32_e32 v0, v13, v54
	v_fma_f32 v0, v12, v53, -v0
	v_add_f32_e32 v40, v40, v0
	v_mul_f32_e32 v0, v15, v56
	v_fma_f32 v0, v14, v55, -v0
	v_add_f32_e32 v40, v40, v0
	v_mul_f32_e32 v0, v17, v58
	v_fma_f32 v0, v16, v57, -v0
	v_add_f32_e32 v40, v40, v0
	v_fmac_f32_e32 v18, v40, v40
	global_load_dword v51, v2, s[0:1] offset:3072
	global_load_dword v52, v3, s[0:1] offset:3072
	global_load_dword v53, v4, s[0:1] offset:3072
	global_load_dword v54, v5, s[0:1] offset:3072
	global_load_dword v55, v6, s[0:1] offset:3072
	global_load_dword v56, v7, s[0:1] offset:3072
	global_load_dword v57, v8, s[0:1] offset:3072
	global_load_dword v58, v9, s[0:1] offset:3072
	s_waitcnt vmcnt(48)
	v_mul_f32_e32 v0, v11, v60
	v_fma_f32 v41, v10, v59, -v0
	v_mul_f32_e32 v0, v13, v62
	v_fma_f32 v0, v12, v61, -v0
	v_add_f32_e32 v41, v41, v0
	v_mul_f32_e32 v0, v15, v64
	v_fma_f32 v0, v14, v63, -v0
	v_add_f32_e32 v41, v41, v0
	v_mul_f32_e32 v0, v17, v66
	v_fma_f32 v0, v16, v65, -v0
	v_add_f32_e32 v41, v41, v0
	v_fmac_f32_e32 v18, v41, v41
	global_load_dword v59, v2, s[0:1] offset:3328
	global_load_dword v60, v3, s[0:1] offset:3328
	global_load_dword v61, v4, s[0:1] offset:3328
	global_load_dword v62, v5, s[0:1] offset:3328
	global_load_dword v63, v6, s[0:1] offset:3328
	global_load_dword v64, v7, s[0:1] offset:3328
	global_load_dword v65, v8, s[0:1] offset:3328
	global_load_dword v66, v9, s[0:1] offset:3328
	s_waitcnt vmcnt(48)
	v_mul_f32_e32 v0, v11, v68
	v_fma_f32 v42, v10, v67, -v0
	v_mul_f32_e32 v0, v13, v70
	v_fma_f32 v0, v12, v69, -v0
	v_add_f32_e32 v42, v42, v0
	v_mul_f32_e32 v0, v15, v72
	v_fma_f32 v0, v14, v71, -v0
	v_add_f32_e32 v42, v42, v0
	v_mul_f32_e32 v0, v17, v74
	v_fma_f32 v0, v16, v73, -v0
	v_add_f32_e32 v42, v42, v0
	v_fmac_f32_e32 v18, v42, v42
	global_load_dword v67, v2, s[0:1] offset:3584
	global_load_dword v68, v3, s[0:1] offset:3584
	global_load_dword v69, v4, s[0:1] offset:3584
	global_load_dword v70, v5, s[0:1] offset:3584
	global_load_dword v71, v6, s[0:1] offset:3584
	global_load_dword v72, v7, s[0:1] offset:3584
	global_load_dword v73, v8, s[0:1] offset:3584
	global_load_dword v74, v9, s[0:1] offset:3584
	s_waitcnt vmcnt(48)
	v_mul_f32_e32 v0, v11, v76
	v_fma_f32 v43, v10, v75, -v0
	v_mul_f32_e32 v0, v13, v78
	v_fma_f32 v0, v12, v77, -v0
	v_add_f32_e32 v43, v43, v0
	v_mul_f32_e32 v0, v15, v80
	v_fma_f32 v0, v14, v79, -v0
	v_add_f32_e32 v43, v43, v0
	v_mul_f32_e32 v0, v17, v82
	v_fma_f32 v0, v16, v81, -v0
	v_add_f32_e32 v43, v43, v0
	v_fmac_f32_e32 v18, v43, v43
	global_load_dword v75, v2, s[0:1] offset:3840
	global_load_dword v76, v3, s[0:1] offset:3840
	global_load_dword v77, v4, s[0:1] offset:3840
	global_load_dword v78, v5, s[0:1] offset:3840
	global_load_dword v79, v6, s[0:1] offset:3840
	global_load_dword v80, v7, s[0:1] offset:3840
	global_load_dword v81, v8, s[0:1] offset:3840
	global_load_dword v82, v9, s[0:1] offset:3840
	s_waitcnt vmcnt(48)
	v_mul_f32_e32 v0, v11, v84
	v_fma_f32 v44, v10, v83, -v0
	v_mul_f32_e32 v0, v13, v86
	v_fma_f32 v0, v12, v85, -v0
	v_add_f32_e32 v44, v44, v0
	v_mul_f32_e32 v0, v15, v88
	v_fma_f32 v0, v14, v87, -v0
	v_add_f32_e32 v44, v44, v0
	v_mul_f32_e32 v0, v17, v90
	v_fma_f32 v0, v16, v89, -v0
	v_add_f32_e32 v44, v44, v0
	v_fmac_f32_e32 v18, v44, v44
	s_waitcnt vmcnt(40)
	v_mul_f32_e32 v0, v11, v92
	v_fma_f32 v45, v10, v91, -v0
	v_mul_f32_e32 v0, v13, v94
	v_fma_f32 v0, v12, v93, -v0
	v_add_f32_e32 v45, v45, v0
	v_mul_f32_e32 v0, v15, v96
	v_fma_f32 v0, v14, v95, -v0
	v_add_f32_e32 v45, v45, v0
	v_mul_f32_e32 v0, v17, v98
	v_fma_f32 v0, v16, v97, -v0
	v_add_f32_e32 v45, v45, v0
	v_fmac_f32_e32 v18, v45, v45
	s_waitcnt vmcnt(32)
	v_mul_f32_e32 v0, v11, v100
	v_fma_f32 v46, v10, v99, -v0
	v_mul_f32_e32 v0, v13, v102
	v_fma_f32 v0, v12, v101, -v0
	v_add_f32_e32 v46, v46, v0
	v_mul_f32_e32 v0, v15, v104
	v_fma_f32 v0, v14, v103, -v0
	v_add_f32_e32 v46, v46, v0
	v_mul_f32_e32 v0, v17, v106
	v_fma_f32 v0, v16, v105, -v0
	v_add_f32_e32 v46, v46, v0
	v_fmac_f32_e32 v18, v46, v46
	s_waitcnt vmcnt(24)
	v_mul_f32_e32 v0, v11, v52
	v_fma_f32 v47, v10, v51, -v0
	v_mul_f32_e32 v0, v13, v54
	v_fma_f32 v0, v12, v53, -v0
	v_add_f32_e32 v47, v47, v0
	v_mul_f32_e32 v0, v15, v56
	v_fma_f32 v0, v14, v55, -v0
	v_add_f32_e32 v47, v47, v0
	v_mul_f32_e32 v0, v17, v58
	v_fma_f32 v0, v16, v57, -v0
	v_add_f32_e32 v47, v47, v0
	v_fmac_f32_e32 v18, v47, v47
	s_waitcnt vmcnt(16)
	v_mul_f32_e32 v0, v11, v60
	v_fma_f32 v48, v10, v59, -v0
	v_mul_f32_e32 v0, v13, v62
	v_fma_f32 v0, v12, v61, -v0
	v_add_f32_e32 v48, v48, v0
	v_mul_f32_e32 v0, v15, v64
	v_fma_f32 v0, v14, v63, -v0
	v_add_f32_e32 v48, v48, v0
	v_mul_f32_e32 v0, v17, v66
	v_fma_f32 v0, v16, v65, -v0
	v_add_f32_e32 v48, v48, v0
	v_fmac_f32_e32 v18, v48, v48
	s_waitcnt vmcnt(8)
	v_mul_f32_e32 v0, v11, v68
	v_fma_f32 v49, v10, v67, -v0
	v_mul_f32_e32 v0, v13, v70
	v_fma_f32 v0, v12, v69, -v0
	v_add_f32_e32 v49, v49, v0
	v_mul_f32_e32 v0, v15, v72
	v_fma_f32 v0, v14, v71, -v0
	v_add_f32_e32 v49, v49, v0
	v_mul_f32_e32 v0, v17, v74
	v_fma_f32 v0, v16, v73, -v0
	v_add_f32_e32 v49, v49, v0
	v_fmac_f32_e32 v18, v49, v49
	s_waitcnt vmcnt(0)
	v_mul_f32_e32 v0, v11, v76
	v_fma_f32 v50, v10, v75, -v0
	v_mul_f32_e32 v0, v13, v78
	v_fma_f32 v0, v12, v77, -v0
	v_add_f32_e32 v50, v50, v0
	v_mul_f32_e32 v0, v15, v80
	v_fma_f32 v0, v14, v79, -v0
	v_add_f32_e32 v50, v50, v0
	v_mul_f32_e32 v0, v17, v82
	v_fma_f32 v0, v16, v81, -v0
	v_add_f32_e32 v50, v50, v0
	v_fmac_f32_e32 v18, v50, v50
	v_and_b32_e32 v51, 16, v219
	v_lshlrev_b32_e32 v52, 4, v51
	v_add_u32_e32 v52, v52, v192
	v_lshlrev_b32_e32 v53, 3, v51
	v_lshl_add_u32 v53, v189, 3, v53
	v_and_b32_e32 v54, 15, v196
	v_min_u32_e32 v55, 15, v196
	v_sub_u32_e32 v54, v54, v55
	v_mul_i32_i24_e32 v54, 0x1800, v54
	v_add_u32_e32 v54, v54, v53
	v_ashrrev_i32_e32 v55, 31, v54
	v_lshl_add_u64 v[54:55], v[54:55], 0, v[194:195]
	global_load_dwordx4 v[56:59], v52, s[24:25] offset:0
	global_load_dwordx4 v[60:63], v52, s[24:25] offset:32
	global_load_dwordx4 v[64:67], v52, s[24:25] offset:64
	global_load_dwordx4 v[68:71], v52, s[24:25] offset:96
	global_load_dwordx4 v[72:75], v52, s[24:25] offset:128
	global_load_dwordx4 v[76:79], v52, s[24:25] offset:160
	global_load_dwordx4 v[80:83], v52, s[24:25] offset:192
	global_load_dwordx4 v[84:87], v52, s[24:25] offset:224
	global_load_dwordx2 v[88:89], v[54:55], off offset:3072
	global_load_dwordx2 v[90:91], v[54:55], off offset:3088
	global_load_dwordx2 v[92:93], v[54:55], off offset:3104
	global_load_dwordx2 v[94:95], v[54:55], off offset:3120
	global_load_dwordx2 v[96:97], v[54:55], off offset:3136
	global_load_dwordx2 v[98:99], v[54:55], off offset:3152
	global_load_dwordx2 v[100:101], v[54:55], off offset:3168
	global_load_dwordx2 v[102:103], v[54:55], off offset:3184
	v_xor_b32_e32 v0, 16, v217
	v_lshlrev_b32_e32 v0, 2, v0
	ds_bpermute_b32 v0, v0, v18
	s_waitcnt lgkmcnt(0)
	v_add_f32_e32 v18, v18, v0
	v_xor_b32_e32 v0, 32, v217
	v_lshlrev_b32_e32 v0, 2, v0
	ds_bpermute_b32 v0, v0, v18
	s_waitcnt lgkmcnt(0)
	v_add_f32_e32 v18, v18, v0
	v_mov_b32_e32 v0, 0x3727c5ac
	v_fmamk_f32 v18, v18, 0x3c000000, v0
	s_mov_b32 s6, 0x800000
	v_cmp_gt_f32_e32 vcc, s6, v18
	v_mul_f32_e32 v0, 0x4b800000, v18
	s_nop 1
	v_cndmask_b32_e32 v18, v18, v0, vcc
	v_rsq_f32_e32 v18, v18
	s_nop 0
	v_mul_f32_e32 v0, 0x45800000, v18
	v_cndmask_b32_e32 v18, v18, v0, vcc
	v_mul_f32_e32 v18, 0x3f4ccccd, v18
	v_and_b32_e32 v0, -16, v191
	v_and_b32_e32 v104, 15, v196
	v_or_b32_e32 v0, v0, v104
	v_lshl_add_u32 v0, v0, 11, v53
	s_lshl_b32 s70, s14, 1
	v_lshl_add_u64 v[104:105], s[62:63], 0, v[0:1]
	v_lshl_add_u64 v[104:105], v[104:105], 0, s[70:71]
	s_waitcnt vmcnt(0)
	v_lshlrev_b32_e32 v2, 16, v88
	v_mul_f32_e32 v6, 0xbfb8aa3b, v2
	v_exp_f32_e32 v6, v6
	v_mul_f32_e32 v19, v19, v18
	v_add_f32_e32 v6, 1.0, v6
	v_rcp_f32_e32 v6, v6
	v_mul_f32_e32 v19, v19, v56
	v_mul_f32_e32 v6, v6, v2
	v_mul_f32_e32 v19, v19, v6
	v_and_b32_e32 v3, 0xffff0000, v88
	v_mul_f32_e32 v7, 0xbfb8aa3b, v3
	v_exp_f32_e32 v7, v7
	v_mul_f32_e32 v20, v20, v18
	v_add_f32_e32 v7, 1.0, v7
	v_rcp_f32_e32 v7, v7
	v_mul_f32_e32 v20, v20, v57
	v_mul_f32_e32 v7, v7, v3
	v_mul_f32_e32 v20, v20, v7
	v_lshlrev_b32_e32 v4, 16, v89
	v_mul_f32_e32 v8, 0xbfb8aa3b, v4
	v_exp_f32_e32 v8, v8
	v_mul_f32_e32 v21, v21, v18
	v_add_f32_e32 v8, 1.0, v8
	v_rcp_f32_e32 v8, v8
	v_mul_f32_e32 v21, v21, v58
	v_mul_f32_e32 v8, v8, v4
	v_mul_f32_e32 v21, v21, v8
	v_and_b32_e32 v5, 0xffff0000, v89
	v_mul_f32_e32 v9, 0xbfb8aa3b, v5
	v_exp_f32_e32 v9, v9
	v_mul_f32_e32 v22, v22, v18
	v_add_f32_e32 v9, 1.0, v9
	v_rcp_f32_e32 v9, v9
	v_mul_f32_e32 v22, v22, v59
	v_mul_f32_e32 v9, v9, v5
	v_mul_f32_e32 v22, v22, v9
	v_cvt_pk_bf16_f32 v10, v19, v20
	v_cvt_pk_bf16_f32 v11, v21, v22
	global_store_dwordx2 v[104:105], v[10:11], off offset:0
	v_lshlrev_b32_e32 v2, 16, v90
	v_mul_f32_e32 v6, 0xbfb8aa3b, v2
	v_exp_f32_e32 v6, v6
	v_mul_f32_e32 v23, v23, v18
	v_add_f32_e32 v6, 1.0, v6
	v_rcp_f32_e32 v6, v6
	v_mul_f32_e32 v23, v23, v60
	v_mul_f32_e32 v6, v6, v2
	v_mul_f32_e32 v23, v23, v6
	v_and_b32_e32 v3, 0xffff0000, v90
	v_mul_f32_e32 v7, 0xbfb8aa3b, v3
	v_exp_f32_e32 v7, v7
	v_mul_f32_e32 v24, v24, v18
	v_add_f32_e32 v7, 1.0, v7
	v_rcp_f32_e32 v7, v7
	v_mul_f32_e32 v24, v24, v61
	v_mul_f32_e32 v7, v7, v3
	v_mul_f32_e32 v24, v24, v7
	v_lshlrev_b32_e32 v4, 16, v91
	v_mul_f32_e32 v8, 0xbfb8aa3b, v4
	v_exp_f32_e32 v8, v8
	v_mul_f32_e32 v25, v25, v18
	v_add_f32_e32 v8, 1.0, v8
	v_rcp_f32_e32 v8, v8
	v_mul_f32_e32 v25, v25, v62
	v_mul_f32_e32 v8, v8, v4
	v_mul_f32_e32 v25, v25, v8
	v_and_b32_e32 v5, 0xffff0000, v91
	v_mul_f32_e32 v9, 0xbfb8aa3b, v5
	v_exp_f32_e32 v9, v9
	v_mul_f32_e32 v26, v26, v18
	v_add_f32_e32 v9, 1.0, v9
	v_rcp_f32_e32 v9, v9
	v_mul_f32_e32 v26, v26, v63
	v_mul_f32_e32 v9, v9, v5
	v_mul_f32_e32 v26, v26, v9
	v_cvt_pk_bf16_f32 v10, v23, v24
	v_cvt_pk_bf16_f32 v11, v25, v26
	global_store_dwordx2 v[104:105], v[10:11], off offset:16
	v_lshlrev_b32_e32 v2, 16, v92
	v_mul_f32_e32 v6, 0xbfb8aa3b, v2
	v_exp_f32_e32 v6, v6
	v_mul_f32_e32 v27, v27, v18
	v_add_f32_e32 v6, 1.0, v6
	v_rcp_f32_e32 v6, v6
	v_mul_f32_e32 v27, v27, v64
	v_mul_f32_e32 v6, v6, v2
	v_mul_f32_e32 v27, v27, v6
	v_and_b32_e32 v3, 0xffff0000, v92
	v_mul_f32_e32 v7, 0xbfb8aa3b, v3
	v_exp_f32_e32 v7, v7
	v_mul_f32_e32 v28, v28, v18
	v_add_f32_e32 v7, 1.0, v7
	v_rcp_f32_e32 v7, v7
	v_mul_f32_e32 v28, v28, v65
	v_mul_f32_e32 v7, v7, v3
	v_mul_f32_e32 v28, v28, v7
	v_lshlrev_b32_e32 v4, 16, v93
	v_mul_f32_e32 v8, 0xbfb8aa3b, v4
	v_exp_f32_e32 v8, v8
	v_mul_f32_e32 v29, v29, v18
	v_add_f32_e32 v8, 1.0, v8
	v_rcp_f32_e32 v8, v8
	v_mul_f32_e32 v29, v29, v66
	v_mul_f32_e32 v8, v8, v4
	v_mul_f32_e32 v29, v29, v8
	v_and_b32_e32 v5, 0xffff0000, v93
	v_mul_f32_e32 v9, 0xbfb8aa3b, v5
	v_exp_f32_e32 v9, v9
	v_mul_f32_e32 v30, v30, v18
	v_add_f32_e32 v9, 1.0, v9
	v_rcp_f32_e32 v9, v9
	v_mul_f32_e32 v30, v30, v67
	v_mul_f32_e32 v9, v9, v5
	v_mul_f32_e32 v30, v30, v9
	v_cvt_pk_bf16_f32 v10, v27, v28
	v_cvt_pk_bf16_f32 v11, v29, v30
	global_store_dwordx2 v[104:105], v[10:11], off offset:32
	v_lshlrev_b32_e32 v2, 16, v94
	v_mul_f32_e32 v6, 0xbfb8aa3b, v2
	v_exp_f32_e32 v6, v6
	v_mul_f32_e32 v31, v31, v18
	v_add_f32_e32 v6, 1.0, v6
	v_rcp_f32_e32 v6, v6
	v_mul_f32_e32 v31, v31, v68
	v_mul_f32_e32 v6, v6, v2
	v_mul_f32_e32 v31, v31, v6
	v_and_b32_e32 v3, 0xffff0000, v94
	v_mul_f32_e32 v7, 0xbfb8aa3b, v3
	v_exp_f32_e32 v7, v7
	v_mul_f32_e32 v32, v32, v18
	v_add_f32_e32 v7, 1.0, v7
	v_rcp_f32_e32 v7, v7
	v_mul_f32_e32 v32, v32, v69
	v_mul_f32_e32 v7, v7, v3
	v_mul_f32_e32 v32, v32, v7
	v_lshlrev_b32_e32 v4, 16, v95
	v_mul_f32_e32 v8, 0xbfb8aa3b, v4
	v_exp_f32_e32 v8, v8
	v_mul_f32_e32 v33, v33, v18
	v_add_f32_e32 v8, 1.0, v8
	v_rcp_f32_e32 v8, v8
	v_mul_f32_e32 v33, v33, v70
	v_mul_f32_e32 v8, v8, v4
	v_mul_f32_e32 v33, v33, v8
	v_and_b32_e32 v5, 0xffff0000, v95
	v_mul_f32_e32 v9, 0xbfb8aa3b, v5
	v_exp_f32_e32 v9, v9
	v_mul_f32_e32 v34, v34, v18
	v_add_f32_e32 v9, 1.0, v9
	v_rcp_f32_e32 v9, v9
	v_mul_f32_e32 v34, v34, v71
	v_mul_f32_e32 v9, v9, v5
	v_mul_f32_e32 v34, v34, v9
	v_cvt_pk_bf16_f32 v10, v31, v32
	v_cvt_pk_bf16_f32 v11, v33, v34
	global_store_dwordx2 v[104:105], v[10:11], off offset:48
	v_lshlrev_b32_e32 v2, 16, v96
	v_mul_f32_e32 v6, 0xbfb8aa3b, v2
	v_exp_f32_e32 v6, v6
	v_mul_f32_e32 v35, v35, v18
	v_add_f32_e32 v6, 1.0, v6
	v_rcp_f32_e32 v6, v6
	v_mul_f32_e32 v35, v35, v72
	v_mul_f32_e32 v6, v6, v2
	v_mul_f32_e32 v35, v35, v6
	v_and_b32_e32 v3, 0xffff0000, v96
	v_mul_f32_e32 v7, 0xbfb8aa3b, v3
	v_exp_f32_e32 v7, v7
	v_mul_f32_e32 v36, v36, v18
	v_add_f32_e32 v7, 1.0, v7
	v_rcp_f32_e32 v7, v7
	v_mul_f32_e32 v36, v36, v73
	v_mul_f32_e32 v7, v7, v3
	v_mul_f32_e32 v36, v36, v7
	v_lshlrev_b32_e32 v4, 16, v97
	v_mul_f32_e32 v8, 0xbfb8aa3b, v4
	v_exp_f32_e32 v8, v8
	v_mul_f32_e32 v37, v37, v18
	v_add_f32_e32 v8, 1.0, v8
	v_rcp_f32_e32 v8, v8
	v_mul_f32_e32 v37, v37, v74
	v_mul_f32_e32 v8, v8, v4
	v_mul_f32_e32 v37, v37, v8
	v_and_b32_e32 v5, 0xffff0000, v97
	v_mul_f32_e32 v9, 0xbfb8aa3b, v5
	v_exp_f32_e32 v9, v9
	v_mul_f32_e32 v38, v38, v18
	v_add_f32_e32 v9, 1.0, v9
	v_rcp_f32_e32 v9, v9
	v_mul_f32_e32 v38, v38, v75
	v_mul_f32_e32 v9, v9, v5
	v_mul_f32_e32 v38, v38, v9
	v_cvt_pk_bf16_f32 v10, v35, v36
	v_cvt_pk_bf16_f32 v11, v37, v38
	global_store_dwordx2 v[104:105], v[10:11], off offset:64
	v_lshlrev_b32_e32 v2, 16, v98
	v_mul_f32_e32 v6, 0xbfb8aa3b, v2
	v_exp_f32_e32 v6, v6
	v_mul_f32_e32 v39, v39, v18
	v_add_f32_e32 v6, 1.0, v6
	v_rcp_f32_e32 v6, v6
	v_mul_f32_e32 v39, v39, v76
	v_mul_f32_e32 v6, v6, v2
	v_mul_f32_e32 v39, v39, v6
	v_and_b32_e32 v3, 0xffff0000, v98
	v_mul_f32_e32 v7, 0xbfb8aa3b, v3
	v_exp_f32_e32 v7, v7
	v_mul_f32_e32 v40, v40, v18
	v_add_f32_e32 v7, 1.0, v7
	v_rcp_f32_e32 v7, v7
	v_mul_f32_e32 v40, v40, v77
	v_mul_f32_e32 v7, v7, v3
	v_mul_f32_e32 v40, v40, v7
	v_lshlrev_b32_e32 v4, 16, v99
	v_mul_f32_e32 v8, 0xbfb8aa3b, v4
	v_exp_f32_e32 v8, v8
	v_mul_f32_e32 v41, v41, v18
	v_add_f32_e32 v8, 1.0, v8
	v_rcp_f32_e32 v8, v8
	v_mul_f32_e32 v41, v41, v78
	v_mul_f32_e32 v8, v8, v4
	v_mul_f32_e32 v41, v41, v8
	v_and_b32_e32 v5, 0xffff0000, v99
	v_mul_f32_e32 v9, 0xbfb8aa3b, v5
	v_exp_f32_e32 v9, v9
	v_mul_f32_e32 v42, v42, v18
	v_add_f32_e32 v9, 1.0, v9
	v_rcp_f32_e32 v9, v9
	v_mul_f32_e32 v42, v42, v79
	v_mul_f32_e32 v9, v9, v5
	v_mul_f32_e32 v42, v42, v9
	v_cvt_pk_bf16_f32 v10, v39, v40
	v_cvt_pk_bf16_f32 v11, v41, v42
	global_store_dwordx2 v[104:105], v[10:11], off offset:80
	v_lshlrev_b32_e32 v2, 16, v100
	v_mul_f32_e32 v6, 0xbfb8aa3b, v2
	v_exp_f32_e32 v6, v6
	v_mul_f32_e32 v43, v43, v18
	v_add_f32_e32 v6, 1.0, v6
	v_rcp_f32_e32 v6, v6
	v_mul_f32_e32 v43, v43, v80
	v_mul_f32_e32 v6, v6, v2
	v_mul_f32_e32 v43, v43, v6
	v_and_b32_e32 v3, 0xffff0000, v100
	v_mul_f32_e32 v7, 0xbfb8aa3b, v3
	v_exp_f32_e32 v7, v7
	v_mul_f32_e32 v44, v44, v18
	v_add_f32_e32 v7, 1.0, v7
	v_rcp_f32_e32 v7, v7
	v_mul_f32_e32 v44, v44, v81
	v_mul_f32_e32 v7, v7, v3
	v_mul_f32_e32 v44, v44, v7
	v_lshlrev_b32_e32 v4, 16, v101
	v_mul_f32_e32 v8, 0xbfb8aa3b, v4
	v_exp_f32_e32 v8, v8
	v_mul_f32_e32 v45, v45, v18
	v_add_f32_e32 v8, 1.0, v8
	v_rcp_f32_e32 v8, v8
	v_mul_f32_e32 v45, v45, v82
	v_mul_f32_e32 v8, v8, v4
	v_mul_f32_e32 v45, v45, v8
	v_and_b32_e32 v5, 0xffff0000, v101
	v_mul_f32_e32 v9, 0xbfb8aa3b, v5
	v_exp_f32_e32 v9, v9
	v_mul_f32_e32 v46, v46, v18
	v_add_f32_e32 v9, 1.0, v9
	v_rcp_f32_e32 v9, v9
	v_mul_f32_e32 v46, v46, v83
	v_mul_f32_e32 v9, v9, v5
	v_mul_f32_e32 v46, v46, v9
	v_cvt_pk_bf16_f32 v10, v43, v44
	v_cvt_pk_bf16_f32 v11, v45, v46
	global_store_dwordx2 v[104:105], v[10:11], off offset:96
	v_lshlrev_b32_e32 v2, 16, v102
	v_mul_f32_e32 v6, 0xbfb8aa3b, v2
	v_exp_f32_e32 v6, v6
	v_mul_f32_e32 v47, v47, v18
	v_add_f32_e32 v6, 1.0, v6
	v_rcp_f32_e32 v6, v6
	v_mul_f32_e32 v47, v47, v84
	v_mul_f32_e32 v6, v6, v2
	v_mul_f32_e32 v47, v47, v6
	v_and_b32_e32 v3, 0xffff0000, v102
	v_mul_f32_e32 v7, 0xbfb8aa3b, v3
	v_exp_f32_e32 v7, v7
	v_mul_f32_e32 v48, v48, v18
	v_add_f32_e32 v7, 1.0, v7
	v_rcp_f32_e32 v7, v7
	v_mul_f32_e32 v48, v48, v85
	v_mul_f32_e32 v7, v7, v3
	v_mul_f32_e32 v48, v48, v7
	v_lshlrev_b32_e32 v4, 16, v103
	v_mul_f32_e32 v8, 0xbfb8aa3b, v4
	v_exp_f32_e32 v8, v8
	v_mul_f32_e32 v49, v49, v18
	v_add_f32_e32 v8, 1.0, v8
	v_rcp_f32_e32 v8, v8
	v_mul_f32_e32 v49, v49, v86
	v_mul_f32_e32 v8, v8, v4
	v_mul_f32_e32 v49, v49, v8
	v_and_b32_e32 v5, 0xffff0000, v103
	v_mul_f32_e32 v9, 0xbfb8aa3b, v5
	v_exp_f32_e32 v9, v9
	v_mul_f32_e32 v50, v50, v18
	v_add_f32_e32 v9, 1.0, v9
	v_rcp_f32_e32 v9, v9
	v_mul_f32_e32 v50, v50, v87
	v_mul_f32_e32 v9, v9, v5
	v_mul_f32_e32 v50, v50, v9
	v_cvt_pk_bf16_f32 v10, v47, v48
	v_cvt_pk_bf16_f32 v11, v49, v50
	global_store_dwordx2 v[104:105], v[10:11], off offset:112
	s_branch .LBB0_508
